# combo12 with all sample-scan items moved to the 60 workgroups without a b_gate GEMM unit
# speedup vs baseline: 1.0115x; 1.0115x over previous
; #define LAS __attribute__((address_space(3)))
; template <bool PROMPT>
; __device__ __forceinline__ void scan_block(const Params& p, LAS unsigned char* lds, int chs0, int nsteps, const float* s0, float* sfin, int rowbase, int ntok, int h, int half) {
;     const int tid = threadIdx.x, lane = tid & 63, wid = tid >> 6, fr = lane & 15, fq = lane >> 4, slice = half * 4 + (wid & 3), dv = slice * 16 + fr;
;     const bool comp = wid < 4;
;     const unsigned char* dn = (const unsigned char*)p.out;
;     ...
;     if (!comp) {
;         const int t = tid - 256, wrow = t >> 4, wc = t & 15, krow = t >> 3, kc = t & 7;
; __device__ __forceinline__ void phase_scan(const Params& p, LAS unsigned char* lds) {
;     if (blockIdx.x < 64) {
;         const int pair = blockIdx.x >> 1, half = blockIdx.x & 1, b = pair >> 2, h = pair & 3;
;         scan_block<true>(p, lds, pair * 32, 32, nullptr, p.out + O_PBS + (size_t)pair * 16384, b * 2048, 64, h, half);
;     } else {
;         const int bi = blockIdx.x - 64, nb = gridDim.x - 64;
;         for (int s2 = bi; s2 < 256; s2 += nb) { const int s = s2 >> 1, half = s2 & 1, b = s >> 2, h = s & 3;
;             scan_block<false>(p, lds, 1024 + s, 1, p.in[4] + (size_t)s * 16384, p.out + O_SBS + (size_t)s * 16384, MP + b * 16, 16, h, half); }
.LBB0_439:
	s_cmp_lt_i32 s84, 4
	s_cselect_b64 s[12:13], -1, 0
	s_and_b64 s[0:1], s[12:13], s[2:3]
	s_andn2_b64 vcc, exec, s[0:1]
	s_cbranch_vccnz .LBB0_605
	s_cmp_gt_u32 s33, 63
	s_mov_b64 s[0:1], -1
	s_cbranch_scc0 .LBB0_596
	s_sub_i32 s30, s33, 64
	s_sub_i32 s31, s86, 64
	s_movk_i32 s0, 0xff
	s_cmpk_gt_i32 s30, 0xff
	v_and_b32_e32 v53, 15, v184
	s_cbranch_scc1 .LBB0_512
	s_add_u32 s22, s48, 0x461c000
	s_addc_u32 s23, s49, 0
	v_add_u32_e32 v0, 0xffffff00, v184
	s_cmp_lg_u64 s[60:61], 0
	v_lshrrev_b32_e32 v1, 4, v184
	v_bfe_u32 v2, v184, 4, 2
	v_lshrrev_b32_e32 v9, 4, v0
	v_lshrrev_b32_e32 v12, 3, v0
	v_lshlrev_b32_e32 v4, 4, v53
	v_lshlrev_b32_e32 v0, 4, v184
	v_mov_b32_e32 v5, 0
	s_cselect_b64 s[6:7], -1, 0
	s_add_u32 s24, s50, 0xbee8800
	v_lshrrev_b32_e32 v8, 2, v184
	v_cmp_lt_u32_e64 s[2:3], s0, v184
	v_add_u32_e32 v16, 0, v4
	v_and_b32_e32 v0, 0x70, v0
	s_movk_i32 s0, 0x110
	s_movk_i32 s1, 0x90
	v_lshlrev_b32_e32 v6, 2, v2
	v_lshlrev_b32_e32 v7, 9, v2
	v_lshlrev_b32_e32 v57, 9, v1
	v_lshlrev_b32_e32 v62, 4, v2
	v_lshl_add_u64 v[2:3], s[48:49], 0, v[4:5]
	v_mov_b32_e32 v1, v5
	s_addc_u32 s25, s51, 0
	v_lshlrev_b32_e32 v4, 8, v9
	v_add_u32_e32 v17, 0, v0
	v_mul_lo_u32 v18, v9, s0
	v_mul_lo_u32 v19, v12, s1
	v_mad_u32_u24 v21, v53, s0, 0
	v_mad_u32_u24 v63, v53, s1, 0
	v_lshl_add_u64 v[0:1], s[48:49], 0, v[0:1]
	s_add_u32 s26, s50, 0xd0e8800
	v_and_or_b32 v74, v8, 48, v53
	v_lshl_add_u64 v[8:9], v[2:3], 0, v[4:5]
	s_mov_b64 s[0:1], 0x1200000
	v_lshlrev_b32_e32 v4, 7, v12
	s_addc_u32 s27, s51, 0
	v_lshl_add_u64 v[10:11], v[8:9], 0, s[0:1]
	v_lshl_add_u64 v[0:1], v[0:1], 0, v[4:5]
	s_mov_b64 s[0:1], 0x2400000
	s_add_u32 s8, s50, 0x9b40000
	v_lshl_add_u64 v[12:13], v[0:1], 0, s[0:1]
	s_mov_b64 s[0:1], 0x3600000
	s_addc_u32 s9, s51, 0
	v_lshl_add_u64 v[14:15], v[0:1], 0, s[0:1]
	s_lshl_b32 s0, s33, 6
	v_add_u32_e32 v20, 0, v62
	v_mul_u32_u24_e32 v22, 0x90, v53
	v_add_u32_e32 v23, 0x900, v63
	v_add_u32_e32 v24, 0x1200, v63
	v_or_b32_e32 v64, 1, v6
	v_or_b32_e32 v65, 2, v6
	v_or_b32_e32 v66, 3, v6
	s_add_i32 s28, s0, 0xfffff000
	s_lshl_b32 s29, s86, 6
	s_lshl_b32 s0, s33, 1
	s_lshl_b32 s35, s86, 1
	v_or_b32_e32 v54, 0x800, v7
	s_movk_i32 s20, 0x1000
	v_or_b32_e32 v55, 0x1000, v7
	v_or_b32_e32 v56, 0x1800, v7
	s_movk_i32 s21, 0x2000
	v_or_b32_e32 v58, 0x2000, v7
	v_or_b32_e32 v59, 0x2800, v7
	v_or_b32_e32 v60, 0x3000, v7
	v_or_b32_e32 v61, 0x3800, v7
	v_lshlrev_b32_e32 v67, 7, v64
	v_lshlrev_b32_e32 v68, 7, v65
	v_lshlrev_b32_e32 v69, 7, v66
	v_or_b32_e32 v70, 0x1880, v57
	v_or_b32_e32 v71, 0x1900, v57
	v_or_b32_e32 v72, 0x1980, v57
	v_or_b32_e32 v73, 0x3880, v57
	s_addk_i32 s29, 0xf000
	s_add_i32 s34, s0, 0xffffff80
	s_addk_i32 s35, 0xff80
	v_add_u32_e32 v75, v16, v18
	v_add_u32_e32 v76, v17, v19
	s_movk_i32 s36, 0x4000
	s_mov_b32 s37, 0x8000
	s_mov_b32 s38, 0xa000
	s_mov_b32 s39, 0xc000
	v_add_u32_e32 v77, v21, v62
	v_add_u32_e32 v78, v20, v22
	v_add_u32_e32 v79, v23, v62
	v_add_u32_e32 v80, v24, v62
	v_cndmask_b32_e64 v81, 0, 1, s[6:7]
	s_sub_i32 s40, s30, 0x84
	s_cmp_lt_i32 s40, 0
	s_cbranch_scc1 .LBB0_512
	s_lshl_b32 s28, s40, 6
	s_lshl_b32 s34, s40, 1
	s_branch .LBB0_445

; #define SC_BAR() do { asm volatile("s_waitcnt lgkmcnt(0)" ::: "memory"); __builtin_amdgcn_s_barrier(); asm volatile("" ::: "memory"); } while (0)
; template <bool PROMPT>
; __device__ __forceinline__ void scan_block(const Params& p, LAS unsigned char* lds, int chs0, int nsteps, const float* s0, float* sfin, int rowbase, int ntok, int h, int half) {
;     ...
;         SC_LOAD(A, chs0);
;         SC_STORE(A, 0);
;         SC_BAR();
; __device__ __forceinline__ void phase_scan(const Params& p, LAS unsigned char* lds) {
;     ...
;         for (int s2 = bi; s2 < 256; s2 += nb) { const int s = s2 >> 1, half = s2 & 1, b = s >> 2, h = s & 3;
;             scan_block<false>(p, lds, 1024 + s, 1, p.in[4] + (size_t)s * 16384, p.out + O_SBS + (size_t)s * 16384, MP + b * 16, 16, h, half); }
.LBB0_444:
	s_or_b64 exec, exec, s[10:11]
	s_add_i32 s40, s40, 60
	s_addk_i32 s28, 0xf00
	s_addk_i32 s34, 0x78
	s_cmpk_gt_i32 s40, 0xff
	s_cbranch_scc1 .LBB0_512
.LBB0_445:
	s_ashr_i32 s14, s40, 1
	s_add_i32 s16, s14, 0x400
	s_and_saveexec_b64 s[0:1], s[2:3]
	s_xor_b64 s[4:5], exec, s[0:1]
	s_cbranch_execz .LBB0_447
	s_ashr_i32 s17, s16, 31
	s_lshl_b64 s[10:11], s[16:17], 14
	v_lshl_add_u64 v[44:45], v[8:9], 0, s[10:11]
	v_add_co_u32_e32 v24, vcc, 0x1000, v44
	v_lshl_add_u64 v[82:83], v[10:11], 0, s[10:11]
	s_nop 0
	v_addc_co_u32_e32 v25, vcc, 0, v45, vcc
	v_add_co_u32_e32 v28, vcc, 0x1000, v82
	v_lshl_add_u64 v[84:85], v[12:13], 0, s[10:11]
	s_nop 0
	v_addc_co_u32_e32 v29, vcc, 0, v83, vcc
	v_add_co_u32_e32 v32, vcc, 0x1000, v84
	global_load_dwordx4 v[0:3], v[44:45], off
	global_load_dwordx4 v[16:19], v[82:83], off
	v_addc_co_u32_e32 v33, vcc, 0, v85, vcc
	v_add_co_u32_e32 v36, vcc, 0x2000, v44
	global_load_dwordx4 v[20:23], v[84:85], off
	s_nop 0
	global_load_dwordx4 v[24:27], v[24:25], off
	v_addc_co_u32_e32 v37, vcc, 0, v45, vcc
	v_add_co_u32_e32 v40, vcc, 0x2000, v82
	global_load_dwordx4 v[28:31], v[28:29], off
	s_nop 0
	global_load_dwordx4 v[32:35], v[32:33], off
	v_addc_co_u32_e32 v41, vcc, 0, v83, vcc
	v_add_co_u32_e32 v46, vcc, 0x2000, v84
	global_load_dwordx4 v[36:39], v[36:37], off
	s_nop 0
	global_load_dwordx4 v[40:43], v[40:41], off
	v_addc_co_u32_e32 v47, vcc, 0, v85, vcc
	v_add_co_u32_e32 v48, vcc, 0x3000, v44
	s_lshl_b64 s[0:1], s[16:17], 13
	s_nop 0
	v_addc_co_u32_e32 v49, vcc, 0, v45, vcc
	v_add_co_u32_e32 v82, vcc, 0x3000, v82
	global_load_dwordx4 v[44:47], v[46:47], off
	s_nop 0
	global_load_dwordx4 v[48:51], v[48:49], off
	v_addc_co_u32_e32 v83, vcc, 0, v83, vcc
	v_add_co_u32_e32 v86, vcc, 0x3000, v84
	v_lshl_add_u64 v[94:95], v[14:15], 0, s[0:1]
	s_nop 0
	v_addc_co_u32_e32 v87, vcc, 0, v85, vcc
	global_load_dwordx4 v[82:85], v[82:83], off
	s_nop 0
	global_load_dwordx4 v[86:89], v[86:87], off
	s_nop 0
	global_load_dwordx4 v[90:93], v[94:95], off
	v_add_co_u32_e32 v94, vcc, s20, v94
	s_nop 1
	v_addc_co_u32_e32 v95, vcc, 0, v95, vcc
	global_load_dwordx4 v[94:97], v[94:95], off
	s_waitcnt vmcnt(0)
	ds_write_b128 v75, v[0:3]
	ds_write_b128 v75, v[16:19] offset:17408
	ds_write_b128 v76, v[20:23] offset:34816
	ds_write_b128 v75, v[24:27] offset:4352
	ds_write_b128 v75, v[28:31] offset:21760
	ds_write_b128 v76, v[32:35] offset:39424
	ds_write_b128 v75, v[36:39] offset:8704
	ds_write_b128 v75, v[40:43] offset:26112
	ds_write_b128 v76, v[44:47] offset:44032
	ds_write_b128 v75, v[48:51] offset:13056
	ds_write_b128 v75, v[82:85] offset:30464
	ds_write_b128 v76, v[90:93] offset:53248
	ds_write_b128 v76, v[86:89] offset:48640
	ds_write_b128 v76, v[94:97] offset:57856
	s_waitcnt lgkmcnt(0)
	s_barrier
	s_waitcnt lgkmcnt(0)
	s_barrier
